# scan-loop counted vmcnt + hand-written SW prompt attention item (loads hoisted)
# speedup vs baseline: 1.0125x; 1.0125x over previous
; #define MFMA(a, b, c) __builtin_amdgcn_mfma_f32_16x16x32_bf16((a), (b), (c), 0, 0, 0)
; DI void sw_prompt_wave(const Params& p, int item) {
;   const int lane = threadIdx.x & 63, r = lane & 15, kg = lane >> 4;
;   const int qt = item & 511, gbh = item >> 9;
;   const int h = gbh & 3, b = (gbh >> 2) & 3, g = gbh >> 4;
;   const int dsh = 2 * g, ln = SEQ >> dsh;
;   const int pos0 = qt * 16, rres = pos0 / ln, i0 = pos0 % ln;
;   const int kbase = i0 - 144;
;   const size_t rb = (size_t)b * SEQ;
;   const int qoff = 2048 + g * 768 + h * 64, koff = qoff + 256;
;   bf16x8 qf[2];
;   {
;     const size_t tok = rb + ((size_t)(i0 + r) << dsh) + rres;
; #pragma unroll
;     for (int ks = 0; ks < 2; ++ks) qf[ks] = *(const bf16x8*)&p.proj[tok * NP + qoff + ks * 32 + kg * 8];
;   }
;   f32x4 st[10];
; #pragma unroll
;   for (int mt = 0; mt < 10; ++mt) {
;     int ki = kbase + mt * 16 + r; ki = ki < 0 ? 0 : ki;
;     const size_t tok = rb + ((size_t)ki << dsh) + rres;
;     f32x4 a = (f32x4){0.f, 0.f, 0.f, 0.f};
; #pragma unroll
;     for (int ks = 0; ks < 2; ++ks) {
;       bf16x8 kf = *(const bf16x8*)&p.proj[tok * NP + koff + ks * 32 + kg * 8];
;       a = MFMA(kf, qf[ks], a);
;     }
;     st[mt] = a;
;   }
;     ...
;     const u16* vrow = &p.vT[((size_t)gbh * 64 + nt * 16 + r) * SEQ + (size_t)rres * ln];
; #pragma unroll
;     for (int k2 = 0; k2 < 5; ++k2) {
;       int ka = kbase + k2 * 32 + kg * 4, kc = ka + 16;
;       ka = ka < 0 ? 0 : ka; kc = kc < 0 ? 0 : kc;
;       uint2 va = *(const uint2*)&vrow[ka];
.LBB0_617:
	v_readfirstlane_b32 s24, v9
	v_mov_b32_e32 v194, 0x101c0
	v_mov_b32_e32 v195, 0x10160
	ds_read_b128 v[128:131], v194
	ds_read_b64 v[168:169], v195
	s_and_b32 s25, s24, 0x1ff
	s_lshr_b32 s26, s24, 9
	s_and_b32 s27, s26, 3
	s_bfe_u32 s28, s26, 0x20002
	s_lshr_b32 s29, s26, 4
	s_lshl_b32 s30, s29, 1
	s_sub_i32 s31, 13, s30
	s_lshl_b32 s25, s25, 4
	s_lshr_b32 s34, s25, s31
	s_lshl_b32 s35, s34, s31
	s_sub_i32 s35, s25, s35
	s_add_i32 s36, s35, 0xffffff70
	s_lshl_b32 s37, s28, 13
	s_add_i32 s37, s37, s34
	v_add_u32_e32 v197, s35, v134
	v_lshlrev_b32_e32 v197, s30, v197
	v_add_u32_e32 v252, s37, v197
	v_mul_u32_u24_e32 v197, 0x2200, v252
	v_lshl_add_u32 v203, v175, 4, v197
	v_add_u32_e32 v254, s36, v134
	v_add_u32_e32 v24, 0x10, v254
	v_max_i32_e32 v24, 0, v24
	v_lshlrev_b32_e32 v24, s30, v24
	v_add_u32_e32 v24, s37, v24
	v_mul_u32_u24_e32 v24, 0x2200, v24
	v_lshl_add_u32 v24, v175, 4, v24
	v_add_u32_e32 v25, 0x20, v254
	v_max_i32_e32 v25, 0, v25
	v_lshlrev_b32_e32 v25, s30, v25
	v_add_u32_e32 v25, s37, v25
	v_mul_u32_u24_e32 v25, 0x2200, v25
	v_lshl_add_u32 v25, v175, 4, v25
	v_add_u32_e32 v26, 0x30, v254
	v_max_i32_e32 v26, 0, v26
	v_lshlrev_b32_e32 v26, s30, v26
	v_add_u32_e32 v26, s37, v26
	v_mul_u32_u24_e32 v26, 0x2200, v26
	v_lshl_add_u32 v26, v175, 4, v26
	v_add_u32_e32 v27, 0x40, v254
	v_max_i32_e32 v27, 0, v27
	v_lshlrev_b32_e32 v27, s30, v27
	v_add_u32_e32 v27, s37, v27
	v_mul_u32_u24_e32 v27, 0x2200, v27
	v_lshl_add_u32 v27, v175, 4, v27
	v_add_u32_e32 v28, 0x50, v254
	v_max_i32_e32 v28, 0, v28
	v_lshlrev_b32_e32 v28, s30, v28
	v_add_u32_e32 v28, s37, v28
	v_mul_u32_u24_e32 v28, 0x2200, v28
	v_lshl_add_u32 v28, v175, 4, v28
	v_add_u32_e32 v29, 0x60, v254
	v_max_i32_e32 v29, 0, v29
	v_lshlrev_b32_e32 v29, s30, v29
	v_add_u32_e32 v29, s37, v29
	v_mul_u32_u24_e32 v29, 0x2200, v29
	v_lshl_add_u32 v29, v175, 4, v29
	v_add_u32_e32 v42, 0x70, v254
	v_max_i32_e32 v42, 0, v42
	v_lshlrev_b32_e32 v42, s30, v42
	v_add_u32_e32 v42, s37, v42
	v_mul_u32_u24_e32 v42, 0x2200, v42
	v_lshl_add_u32 v42, v175, 4, v42
	v_add_u32_e32 v43, 0x80, v254
	v_max_i32_e32 v43, 0, v43
	v_lshlrev_b32_e32 v43, s30, v43
	v_add_u32_e32 v43, s37, v43
	v_mul_u32_u24_e32 v43, 0x2200, v43
	v_lshl_add_u32 v43, v175, 4, v43
	v_add_u32_e32 v64, 0x90, v254
	v_max_i32_e32 v64, 0, v64
	v_lshlrev_b32_e32 v64, s30, v64
	v_add_u32_e32 v64, s37, v64
	v_mul_u32_u24_e32 v64, 0x2200, v64
	v_lshl_add_u32 v64, v175, 4, v64
	s_mul_i32 s24, s29, 0x600
	s_lshl_b32 s25, s27, 7
	s_add_i32 s24, s24, s25
	s_addk_i32 s24, 0x1000
	s_waitcnt lgkmcnt(0)
	v_readfirstlane_b32 s40, v168
	v_readfirstlane_b32 s41, v169
	v_readfirstlane_b32 s42, v128
	v_readfirstlane_b32 s43, v129
	v_readfirstlane_b32 s38, v130
	v_readfirstlane_b32 s39, v131
	s_nop 3
	s_add_u32 s40, s40, s24
	s_addc_u32 s41, s41, 0
	s_lshl_b32 s24, s26, 20
	s_lshl_b32 s25, s34, s31
	s_lshl_b32 s25, s25, 1
	s_add_i32 s24, s24, s25
	s_add_u32 s42, s42, s24
	s_addc_u32 s43, s43, 0
	s_add_u32 s44, s42, 0x40000
	s_addc_u32 s45, s43, 0
	s_add_u32 s46, s44, 0x40000
	s_addc_u32 s47, s45, 0
	s_add_u32 s48, s46, 0x40000
	s_addc_u32 s49, s47, 0
	s_mul_i32 s24, s29, 0x1010000
	s_lshl_b32 s28, s27, 7
	s_add_i32 s24, s24, s28
	s_add_u32 s38, s38, s24
	s_addc_u32 s39, s39, 0
	s_nop 1
	global_load_dwordx4 v[76:79], v203, s[40:41]
	global_load_dwordx4 v[80:83], v203, s[40:41] offset:64
	global_load_dwordx4 v[204:207], v24, s[40:41] offset:512
	global_load_dwordx4 v[208:211], v24, s[40:41] offset:576
	global_load_dwordx4 v[212:215], v25, s[40:41] offset:512
	global_load_dwordx4 v[216:219], v25, s[40:41] offset:576
	global_load_dwordx4 v[220:223], v26, s[40:41] offset:512
	global_load_dwordx4 v[224:227], v26, s[40:41] offset:576
	global_load_dwordx4 v[228:231], v27, s[40:41] offset:512
	global_load_dwordx4 v[232:235], v27, s[40:41] offset:576
	global_load_dwordx4 v[236:239], v28, s[40:41] offset:512
	global_load_dwordx4 v[240:243], v28, s[40:41] offset:576
	global_load_dwordx4 v[244:247], v29, s[40:41] offset:512
	global_load_dwordx4 v[248:251], v29, s[40:41] offset:576
	global_load_dwordx4 v[104:107], v42, s[40:41] offset:512
	global_load_dwordx4 v[108:111], v42, s[40:41] offset:576
	global_load_dwordx4 v[112:115], v43, s[40:41] offset:512
	global_load_dwordx4 v[116:119], v43, s[40:41] offset:576
	global_load_dwordx4 v[120:123], v64, s[40:41] offset:512
	global_load_dwordx4 v[124:127], v64, s[40:41] offset:576
	v_lshlrev_b32_e32 v197, 14, v134
	v_add_u32_e32 v254, s36, v170
	v_max_i32_e32 v66, 0, v254
	v_lshl_add_u32 v66, v66, 1, v197
	v_add_u32_e32 v69, 0x10, v254
	v_max_i32_e32 v69, 0, v69
	v_lshl_add_u32 v69, v69, 1, v197
	v_add_u32_e32 v70, 0x20, v254
	v_max_i32_e32 v70, 0, v70
	v_lshl_add_u32 v70, v70, 1, v197
	v_add_u32_e32 v72, 0x30, v254
	v_max_i32_e32 v72, 0, v72
	v_lshl_add_u32 v72, v72, 1, v197
	v_add_u32_e32 v74, 0x40, v254
	v_max_i32_e32 v74, 0, v74
	v_lshl_add_u32 v74, v74, 1, v197
	v_add_u32_e32 v141, 0x50, v254
	v_max_i32_e32 v141, 0, v141
	v_lshl_add_u32 v141, v141, 1, v197
	v_add_u32_e32 v145, 0x60, v254
	v_max_i32_e32 v145, 0, v145
	v_lshl_add_u32 v145, v145, 1, v197
	v_add_u32_e32 v147, 0x70, v254
	v_max_i32_e32 v147, 0, v147
	v_lshl_add_u32 v147, v147, 1, v197
	v_add_u32_e32 v151, 0x80, v254
	v_max_i32_e32 v151, 0, v151
	v_lshl_add_u32 v151, v151, 1, v197
	v_add_u32_e32 v162, 0x90, v254
	v_max_i32_e32 v162, 0, v162
	v_lshl_add_u32 v162, v162, 1, v197
	v_lshlrev_b32_e32 v253, 9, v252
	v_lshl_add_u32 v253, v175, 3, v253
	v_mov_b32_e32 v103, 0xff61b1e6
	v_sub_u32_e32 v64, v170, v134
	v_xor_b32_e32 v194, 16, v99
	v_xor_b32_e32 v195, 32, v99
	s_waitcnt vmcnt(0)
; #define MFMA(a, b, c) __builtin_amdgcn_mfma_f32_16x16x32_bf16((a), (b), (c), 0, 0, 0)
; DI void sw_prompt_wave(const Params& p, int item) {
;     ...
;   for (int mt = 0; mt < 10; ++mt) {
;     int ki = kbase + mt * 16 + r; ki = ki < 0 ? 0 : ki;
;     const size_t tok = rb + ((size_t)ki << dsh) + rres;
;     f32x4 a = (f32x4){0.f, 0.f, 0.f, 0.f};
; #pragma unroll
;     for (int ks = 0; ks < 2; ++ks) {
;       bf16x8 kf = *(const bf16x8*)&p.proj[tok * NP + koff + ks * 32 + kg * 8];
;       a = MFMA(kf, qf[ks], a);
;     }
;     st[mt] = a;
;   }
;   const int qi = i0 + r;
;   float mx = -3.0e38f;
; #pragma unroll
;   for (int mt = 0; mt < 10; ++mt)
; #pragma unroll
;     for (int j = 0; j < 4; ++j) {
;       const int ki = kbase + mt * 16 + kg * 4 + j;
;       const int d = qi - ki;
;       const bool valid = (ki >= 0) && (d >= 0) && (d <= 128);
;       const float sv = valid ? st[mt][j] * 0.125f : -3.0e38f;
;       st[mt][j] = sv;
;       mx = fmaxf(mx, sv);
;     }
;     ...
;     const u16* vrow = &p.vT[((size_t)gbh * 64 + nt * 16 + r) * SEQ + (size_t)rres * ln];
; #pragma unroll
;     for (int k2 = 0; k2 < 5; ++k2) {
;       int ka = kbase + k2 * 32 + kg * 4, kc = ka + 16;
;       ka = ka < 0 ? 0 : ka; kc = kc < 0 ? 0 : kc;
;       uint2 va = *(const uint2*)&vrow[ka];
;       uint2 vc = *(const uint2*)&vrow[kc];
	v_mfma_f32_16x16x32_bf16 v[84:87], v[204:207], v[76:79], 0
	v_mfma_f32_16x16x32_bf16 v[88:91], v[212:215], v[76:79], 0
	v_mfma_f32_16x16x32_bf16 v[44:47], v[220:223], v[76:79], 0
	v_mfma_f32_16x16x32_bf16 v[48:51], v[228:231], v[76:79], 0
	v_mfma_f32_16x16x32_bf16 v[52:55], v[236:239], v[76:79], 0
	v_mfma_f32_16x16x32_bf16 v[56:59], v[244:247], v[76:79], 0
	v_mfma_f32_16x16x32_bf16 v[60:63], v[104:107], v[76:79], 0
	v_mfma_f32_16x16x32_bf16 v[16:19], v[112:115], v[76:79], 0
	v_mfma_f32_16x16x32_bf16 v[20:23], v[120:123], v[76:79], 0
	v_mfma_f32_16x16x32_bf16 v[84:87], v[208:211], v[80:83], v[84:87]
	v_mfma_f32_16x16x32_bf16 v[88:91], v[216:219], v[80:83], v[88:91]
	v_mfma_f32_16x16x32_bf16 v[44:47], v[224:227], v[80:83], v[44:47]
	v_mfma_f32_16x16x32_bf16 v[48:51], v[232:235], v[80:83], v[48:51]
	v_mfma_f32_16x16x32_bf16 v[52:55], v[240:243], v[80:83], v[52:55]
	v_mfma_f32_16x16x32_bf16 v[56:59], v[248:251], v[80:83], v[56:59]
	v_mfma_f32_16x16x32_bf16 v[60:63], v[108:111], v[80:83], v[60:63]
	v_mfma_f32_16x16x32_bf16 v[16:19], v[116:119], v[80:83], v[16:19]
	v_mfma_f32_16x16x32_bf16 v[20:23], v[124:127], v[80:83], v[20:23]
	v_lshlrev_b32_e32 v26, 2, v194
	v_lshlrev_b32_e32 v27, 2, v195
	global_load_dwordx2 v[204:205], v66, s[42:43]
	global_load_dwordx2 v[206:207], v69, s[42:43]
	global_load_dwordx2 v[208:209], v70, s[42:43]
	global_load_dwordx2 v[210:211], v72, s[42:43]
	global_load_dwordx2 v[212:213], v74, s[42:43]
	global_load_dwordx2 v[214:215], v141, s[42:43]
	global_load_dwordx2 v[216:217], v145, s[42:43]
	global_load_dwordx2 v[218:219], v147, s[42:43]
	global_load_dwordx2 v[220:221], v151, s[42:43]
	global_load_dwordx2 v[222:223], v162, s[42:43]
	global_load_dwordx2 v[224:225], v66, s[44:45]
	global_load_dwordx2 v[226:227], v69, s[44:45]
	global_load_dwordx2 v[228:229], v70, s[44:45]
	global_load_dwordx2 v[230:231], v72, s[44:45]
	global_load_dwordx2 v[232:233], v74, s[44:45]
	global_load_dwordx2 v[234:235], v141, s[44:45]
	global_load_dwordx2 v[236:237], v145, s[44:45]
	global_load_dwordx2 v[238:239], v147, s[44:45]
	global_load_dwordx2 v[240:241], v151, s[44:45]
	global_load_dwordx2 v[242:243], v162, s[44:45]
	global_load_dwordx2 v[244:245], v66, s[46:47]
	global_load_dwordx2 v[246:247], v69, s[46:47]
	global_load_dwordx2 v[248:249], v70, s[46:47]
	global_load_dwordx2 v[250:251], v72, s[46:47]
	global_load_dwordx2 v[104:105], v74, s[46:47]
	global_load_dwordx2 v[106:107], v141, s[46:47]
	global_load_dwordx2 v[108:109], v145, s[46:47]
	global_load_dwordx2 v[110:111], v147, s[46:47]
	global_load_dwordx2 v[112:113], v151, s[46:47]
	global_load_dwordx2 v[114:115], v162, s[46:47]
	global_load_dwordx2 v[116:117], v66, s[48:49]
	global_load_dwordx2 v[118:119], v69, s[48:49]
	global_load_dwordx2 v[120:121], v70, s[48:49]
	global_load_dwordx2 v[122:123], v72, s[48:49]
	global_load_dwordx2 v[124:125], v74, s[48:49]
	global_load_dwordx2 v[126:127], v141, s[48:49]
	global_load_dwordx2 v[76:77], v145, s[48:49]
	global_load_dwordx2 v[78:79], v147, s[48:49]
	global_load_dwordx2 v[80:81], v151, s[48:49]
	global_load_dwordx2 v[82:83], v162, s[48:49]
	v_mul_f32_e32 v84, 0x3e000000, v84
	v_mul_f32_e32 v85, 0x3e000000, v85
	v_mul_f32_e32 v86, 0x3e000000, v86
	v_mul_f32_e32 v87, 0x3e000000, v87
	v_mul_f32_e32 v88, 0x3e000000, v88
	v_mul_f32_e32 v89, 0x3e000000, v89
	v_mul_f32_e32 v90, 0x3e000000, v90
	v_mul_f32_e32 v91, 0x3e000000, v91
	v_mul_f32_e32 v44, 0x3e000000, v44
	v_mul_f32_e32 v45, 0x3e000000, v45
	v_mul_f32_e32 v46, 0x3e000000, v46
	v_mul_f32_e32 v47, 0x3e000000, v47
	v_mul_f32_e32 v48, 0x3e000000, v48
	v_mul_f32_e32 v49, 0x3e000000, v49
	v_mul_f32_e32 v50, 0x3e000000, v50
	v_mul_f32_e32 v51, 0x3e000000, v51
	v_mul_f32_e32 v52, 0x3e000000, v52
	v_mul_f32_e32 v53, 0x3e000000, v53
	v_mul_f32_e32 v54, 0x3e000000, v54
	v_mul_f32_e32 v55, 0x3e000000, v55
	v_mul_f32_e32 v56, 0x3e000000, v56
	v_mul_f32_e32 v57, 0x3e000000, v57
	v_mul_f32_e32 v58, 0x3e000000, v58
	v_mul_f32_e32 v59, 0x3e000000, v59
	v_mul_f32_e32 v60, 0x3e000000, v60
	v_mul_f32_e32 v61, 0x3e000000, v61
	v_mul_f32_e32 v62, 0x3e000000, v62
	v_mul_f32_e32 v63, 0x3e000000, v63
	v_mul_f32_e32 v16, 0x3e000000, v16
	v_mul_f32_e32 v17, 0x3e000000, v17
	v_mul_f32_e32 v18, 0x3e000000, v18
	v_mul_f32_e32 v19, 0x3e000000, v19
	v_mul_f32_e32 v20, 0x3e000000, v20
	v_mul_f32_e32 v21, 0x3e000000, v21
	v_mul_f32_e32 v22, 0x3e000000, v22
	v_mul_f32_e32 v23, 0x3e000000, v23
	s_cmp_ge_i32 s36, -16
	s_cbranch_scc1 .Lswp_notile
	s_add_i32 s24, s36, 0x10
	s_cmp_lt_i32 s24, 0
	s_cselect_b64 vcc, -1, 0
	v_cndmask_b32_e32 v84, v84, v103, vcc
	v_cndmask_b32_e32 v85, v85, v103, vcc
	v_cndmask_b32_e32 v86, v86, v103, vcc
	v_cndmask_b32_e32 v87, v87, v103, vcc
	s_add_i32 s24, s36, 0x20
	s_cmp_lt_i32 s24, 0
	s_cselect_b64 vcc, -1, 0
	v_cndmask_b32_e32 v88, v88, v103, vcc
	v_cndmask_b32_e32 v89, v89, v103, vcc
	v_cndmask_b32_e32 v90, v90, v103, vcc
	v_cndmask_b32_e32 v91, v91, v103, vcc
	s_add_i32 s24, s36, 0x30
	s_cmp_lt_i32 s24, 0
	s_cselect_b64 vcc, -1, 0
	v_cndmask_b32_e32 v44, v44, v103, vcc
	v_cndmask_b32_e32 v45, v45, v103, vcc
	v_cndmask_b32_e32 v46, v46, v103, vcc
	v_cndmask_b32_e32 v47, v47, v103, vcc
	s_add_i32 s24, s36, 0x40
	s_cmp_lt_i32 s24, 0
	s_cselect_b64 vcc, -1, 0
	v_cndmask_b32_e32 v48, v48, v103, vcc
	v_cndmask_b32_e32 v49, v49, v103, vcc
	v_cndmask_b32_e32 v50, v50, v103, vcc
	v_cndmask_b32_e32 v51, v51, v103, vcc
	s_add_i32 s24, s36, 0x50
	s_cmp_lt_i32 s24, 0
	s_cselect_b64 vcc, -1, 0
	v_cndmask_b32_e32 v52, v52, v103, vcc
	v_cndmask_b32_e32 v53, v53, v103, vcc
	v_cndmask_b32_e32 v54, v54, v103, vcc
	v_cndmask_b32_e32 v55, v55, v103, vcc
	s_add_i32 s24, s36, 0x60
	s_cmp_lt_i32 s24, 0
	s_cselect_b64 vcc, -1, 0
	v_cndmask_b32_e32 v56, v56, v103, vcc
	v_cndmask_b32_e32 v57, v57, v103, vcc
	v_cndmask_b32_e32 v58, v58, v103, vcc
	v_cndmask_b32_e32 v59, v59, v103, vcc
	s_add_i32 s24, s36, 0x70
	s_cmp_lt_i32 s24, 0
	s_cselect_b64 vcc, -1, 0
	v_cndmask_b32_e32 v60, v60, v103, vcc
	v_cndmask_b32_e32 v61, v61, v103, vcc
	v_cndmask_b32_e32 v62, v62, v103, vcc
	v_cndmask_b32_e32 v63, v63, v103, vcc
	s_add_i32 s24, s36, 0x80
	s_cmp_lt_i32 s24, 0
	s_cselect_b64 vcc, -1, 0
	v_cndmask_b32_e32 v16, v16, v103, vcc
	v_cndmask_b32_e32 v17, v17, v103, vcc
	v_cndmask_b32_e32 v18, v18, v103, vcc
	v_cndmask_b32_e32 v19, v19, v103, vcc
; DI void sw_prompt_wave(const Params& p, int item) {
;     ...
;   const int qi = i0 + r;
;   float mx = -3.0e38f;
; #pragma unroll
;   for (int mt = 0; mt < 10; ++mt)
; #pragma unroll
;     for (int j = 0; j < 4; ++j) {
;       const int ki = kbase + mt * 16 + kg * 4 + j;
;       const int d = qi - ki;
;       const bool valid = (ki >= 0) && (d >= 0) && (d <= 128);
;       const float sv = valid ? st[mt][j] * 0.125f : -3.0e38f;
;       st[mt][j] = sv;
;       mx = fmaxf(mx, sv);
;     }
;   mx = fmaxf(mx, __shfl_xor(mx, 16));
;   mx = fmaxf(mx, __shfl_xor(mx, 32));
;   float sum = 0.f;
; #pragma unroll
;   for (int mt = 0; mt < 10; ++mt)
; #pragma unroll
;     for (int j = 0; j < 4; ++j) {
;       const float pv = (st[mt][j] > -1.0e38f) ? __expf(st[mt][j] - mx) : 0.f;
;       st[mt][j] = pv;
;       sum += pv;
;     }
;   sum += __shfl_xor(sum, 16);
;   sum += __shfl_xor(sum, 32);
.Lswp_notile:
	v_cmp_gt_i32_e32 vcc, 0, v64
	s_nop 1
	v_cndmask_b32_e32 v84, v84, v103, vcc
	v_cmp_gt_i32_e32 vcc, -1, v64
	s_nop 1
	v_cndmask_b32_e32 v85, v85, v103, vcc
	v_cmp_gt_i32_e32 vcc, -2, v64
	s_nop 1
	v_cndmask_b32_e32 v86, v86, v103, vcc
	v_cmp_gt_i32_e32 vcc, -3, v64
	s_nop 1
	v_cndmask_b32_e32 v87, v87, v103, vcc
	v_cmp_lt_i32_e32 vcc, 0, v64
	s_nop 1
	v_cndmask_b32_e32 v20, v20, v103, vcc
	v_cmp_lt_i32_e32 vcc, -1, v64
	s_nop 1
	v_cndmask_b32_e32 v21, v21, v103, vcc
	v_cmp_lt_i32_e32 vcc, -2, v64
	s_nop 1
	v_cndmask_b32_e32 v22, v22, v103, vcc
	v_cmp_lt_i32_e32 vcc, -3, v64
	s_nop 1
	v_cndmask_b32_e32 v23, v23, v103, vcc
	v_max3_f32 v24, v84, v85, v86
	v_max3_f32 v24, v24, v87, v88
	v_max3_f32 v24, v24, v89, v90
	v_max3_f32 v24, v24, v91, v44
	v_max3_f32 v24, v24, v45, v46
	v_max3_f32 v24, v24, v47, v48
	v_max3_f32 v24, v24, v49, v50
	v_max3_f32 v24, v24, v51, v52
	v_max3_f32 v24, v24, v53, v54
	v_max3_f32 v24, v24, v55, v56
	v_max3_f32 v24, v24, v57, v58
	v_max3_f32 v24, v24, v59, v60
	v_max3_f32 v24, v24, v61, v62
	v_max3_f32 v24, v24, v63, v16
	v_max3_f32 v24, v24, v17, v18
	v_max3_f32 v24, v24, v19, v20
	v_max3_f32 v24, v24, v21, v22
	v_max_f32_e32 v24, v24, v23
	s_nop 0
	ds_bpermute_b32 v28, v26, v24
	s_waitcnt lgkmcnt(0)
	v_max_f32_e32 v24, v24, v28
	s_nop 0
	ds_bpermute_b32 v28, v27, v24
	s_waitcnt lgkmcnt(0)
	v_max_f32_e32 v24, v24, v28
	v_sub_f32_e32 v84, v84, v24
	v_sub_f32_e32 v85, v85, v24
	v_sub_f32_e32 v86, v86, v24
	v_sub_f32_e32 v87, v87, v24
	v_sub_f32_e32 v88, v88, v24
	v_sub_f32_e32 v89, v89, v24
	v_sub_f32_e32 v90, v90, v24
	v_sub_f32_e32 v91, v91, v24
	v_sub_f32_e32 v44, v44, v24
	v_sub_f32_e32 v45, v45, v24
	v_sub_f32_e32 v46, v46, v24
	v_sub_f32_e32 v47, v47, v24
	v_sub_f32_e32 v48, v48, v24
	v_sub_f32_e32 v49, v49, v24
	v_sub_f32_e32 v50, v50, v24
	v_sub_f32_e32 v51, v51, v24
	v_sub_f32_e32 v52, v52, v24
	v_sub_f32_e32 v53, v53, v24
	v_sub_f32_e32 v54, v54, v24
	v_sub_f32_e32 v55, v55, v24
	v_sub_f32_e32 v56, v56, v24
	v_sub_f32_e32 v57, v57, v24
	v_sub_f32_e32 v58, v58, v24
	v_sub_f32_e32 v59, v59, v24
	v_sub_f32_e32 v60, v60, v24
	v_sub_f32_e32 v61, v61, v24
	v_sub_f32_e32 v62, v62, v24
	v_sub_f32_e32 v63, v63, v24
	v_sub_f32_e32 v16, v16, v24
	v_sub_f32_e32 v17, v17, v24
	v_sub_f32_e32 v18, v18, v24
	v_sub_f32_e32 v19, v19, v24
	v_sub_f32_e32 v20, v20, v24
	v_sub_f32_e32 v21, v21, v24
	v_sub_f32_e32 v22, v22, v24
	v_sub_f32_e32 v23, v23, v24
	v_mul_f32_e32 v84, 0x3fb8aa3b, v84
	v_mul_f32_e32 v85, 0x3fb8aa3b, v85
	v_mul_f32_e32 v86, 0x3fb8aa3b, v86
	v_mul_f32_e32 v87, 0x3fb8aa3b, v87
	v_mul_f32_e32 v88, 0x3fb8aa3b, v88
	v_mul_f32_e32 v89, 0x3fb8aa3b, v89
	v_mul_f32_e32 v90, 0x3fb8aa3b, v90
	v_mul_f32_e32 v91, 0x3fb8aa3b, v91
	v_mul_f32_e32 v44, 0x3fb8aa3b, v44
	v_mul_f32_e32 v45, 0x3fb8aa3b, v45
	v_mul_f32_e32 v46, 0x3fb8aa3b, v46
	v_mul_f32_e32 v47, 0x3fb8aa3b, v47
	v_mul_f32_e32 v48, 0x3fb8aa3b, v48
	v_mul_f32_e32 v49, 0x3fb8aa3b, v49
	v_mul_f32_e32 v50, 0x3fb8aa3b, v50
	v_mul_f32_e32 v51, 0x3fb8aa3b, v51
	v_mul_f32_e32 v52, 0x3fb8aa3b, v52
	v_mul_f32_e32 v53, 0x3fb8aa3b, v53
	v_mul_f32_e32 v54, 0x3fb8aa3b, v54
	v_mul_f32_e32 v55, 0x3fb8aa3b, v55
	v_mul_f32_e32 v56, 0x3fb8aa3b, v56
	v_mul_f32_e32 v57, 0x3fb8aa3b, v57
	v_mul_f32_e32 v58, 0x3fb8aa3b, v58
	v_mul_f32_e32 v59, 0x3fb8aa3b, v59
	v_mul_f32_e32 v60, 0x3fb8aa3b, v60
	v_mul_f32_e32 v61, 0x3fb8aa3b, v61
	v_mul_f32_e32 v62, 0x3fb8aa3b, v62
	v_mul_f32_e32 v63, 0x3fb8aa3b, v63
	v_mul_f32_e32 v16, 0x3fb8aa3b, v16
	v_mul_f32_e32 v17, 0x3fb8aa3b, v17
	v_mul_f32_e32 v18, 0x3fb8aa3b, v18
	v_mul_f32_e32 v19, 0x3fb8aa3b, v19
	v_mul_f32_e32 v20, 0x3fb8aa3b, v20
	v_mul_f32_e32 v21, 0x3fb8aa3b, v21
	v_mul_f32_e32 v22, 0x3fb8aa3b, v22
	v_mul_f32_e32 v23, 0x3fb8aa3b, v23
	v_exp_f32_e32 v84, v84
	v_exp_f32_e32 v85, v85
	v_exp_f32_e32 v86, v86
	v_exp_f32_e32 v87, v87
	v_exp_f32_e32 v88, v88
	v_exp_f32_e32 v89, v89
	v_exp_f32_e32 v90, v90
	v_exp_f32_e32 v91, v91
	v_exp_f32_e32 v44, v44
	v_exp_f32_e32 v45, v45
	v_exp_f32_e32 v46, v46
	v_exp_f32_e32 v47, v47
	v_exp_f32_e32 v48, v48
	v_exp_f32_e32 v49, v49
	v_exp_f32_e32 v50, v50
	v_exp_f32_e32 v51, v51
	v_exp_f32_e32 v52, v52
	v_exp_f32_e32 v53, v53
	v_exp_f32_e32 v54, v54
	v_exp_f32_e32 v55, v55
	v_exp_f32_e32 v56, v56
	v_exp_f32_e32 v57, v57
	v_exp_f32_e32 v58, v58
	v_exp_f32_e32 v59, v59
	v_exp_f32_e32 v60, v60
	v_exp_f32_e32 v61, v61
	v_exp_f32_e32 v62, v62
	v_exp_f32_e32 v63, v63
	v_exp_f32_e32 v16, v16
	v_exp_f32_e32 v17, v17
	v_exp_f32_e32 v18, v18
	v_exp_f32_e32 v19, v19
	v_exp_f32_e32 v20, v20
	v_exp_f32_e32 v21, v21
	v_exp_f32_e32 v22, v22
	v_exp_f32_e32 v23, v23
	s_nop 0
	v_mov_b32_e32 v25, v84
	v_mov_b32_e32 v29, v85
	v_mov_b32_e32 v42, v86
	v_mov_b32_e32 v43, v87
	v_add_f32_e32 v25, v25, v88
	v_add_f32_e32 v29, v29, v89
	v_add_f32_e32 v42, v42, v90
	v_add_f32_e32 v43, v43, v91
	v_add_f32_e32 v25, v25, v44
	v_add_f32_e32 v29, v29, v45
	v_add_f32_e32 v42, v42, v46
	v_add_f32_e32 v43, v43, v47
	v_add_f32_e32 v25, v25, v48
	v_add_f32_e32 v29, v29, v49
	v_add_f32_e32 v42, v42, v50
	v_add_f32_e32 v43, v43, v51
	v_add_f32_e32 v25, v25, v52
	v_add_f32_e32 v29, v29, v53
	v_add_f32_e32 v42, v42, v54
	v_add_f32_e32 v43, v43, v55
	v_add_f32_e32 v25, v25, v56
	v_add_f32_e32 v29, v29, v57
	v_add_f32_e32 v42, v42, v58
	v_add_f32_e32 v43, v43, v59
	v_add_f32_e32 v25, v25, v60
	v_add_f32_e32 v29, v29, v61
	v_add_f32_e32 v42, v42, v62
	v_add_f32_e32 v43, v43, v63
	v_add_f32_e32 v25, v25, v16
	v_add_f32_e32 v29, v29, v17
	v_add_f32_e32 v42, v42, v18
	v_add_f32_e32 v43, v43, v19
	v_add_f32_e32 v25, v25, v20
	v_add_f32_e32 v29, v29, v21
	v_add_f32_e32 v42, v42, v22
	v_add_f32_e32 v43, v43, v23
	v_add_f32_e32 v25, v25, v29
	v_add_f32_e32 v42, v42, v43
	v_add_f32_e32 v25, v25, v42
	s_nop 0
	ds_bpermute_b32 v28, v26, v25
	s_waitcnt lgkmcnt(0)
; #define MFMA(a, b, c) __builtin_amdgcn_mfma_f32_16x16x32_bf16((a), (b), (c), 0, 0, 0)
; DI unsigned pack2(float a, float b) { return (unsigned)f2bf(a) | ((unsigned)f2bf(b) << 16); }
; DI void sw_prompt_wave(const Params& p, int item) {
;     ...
;   sum += __shfl_xor(sum, 16);
;   sum += __shfl_xor(sum, 32);
;   const float inv = 1.f / sum;
;   bf16x8 pf[5];
; #pragma unroll
;   for (int k2 = 0; k2 < 5; ++k2) pf[k2] = pack8(st[2 * k2], st[2 * k2 + 1]);
;   const size_t qrow = rb + ((size_t)qi << dsh) + rres;
; #pragma unroll
;   for (int nt = 0; nt < 4; ++nt) {
;     f32x4 o = (f32x4){0.f, 0.f, 0.f, 0.f};
;     const u16* vrow = &p.vT[((size_t)gbh * 64 + nt * 16 + r) * SEQ + (size_t)rres * ln];
; #pragma unroll
;     for (int k2 = 0; k2 < 5; ++k2) {
;       int ka = kbase + k2 * 32 + kg * 4, kc = ka + 16;
;       ka = ka < 0 ? 0 : ka; kc = kc < 0 ? 0 : kc;
;       uint2 va = *(const uint2*)&vrow[ka];
;       uint2 vc = *(const uint2*)&vrow[kc];
;       bf16x8 vf = __builtin_bit_cast(bf16x8, make_uint4(va.x, va.y, vc.x, vc.y));
;       o = MFMA(vf, pf[k2], o);
;     }
;     uint2 ov; ov.x = pack2(o[0] * inv, o[1] * inv); ov.y = pack2(o[2] * inv, o[3] * inv);
;     *(uint2*)&p.osw[((size_t)g * MT + qrow) * 256 + h * 64 + nt * 16 + kg * 4] = ov;
;   }
;   if (kg == 0) p.lse[((size_t)g * MT + qrow) * 4 + h] = mx + __logf(sum);
; }
	v_add_f32_e32 v25, v25, v28
	s_nop 0
	ds_bpermute_b32 v28, v27, v25
	s_waitcnt lgkmcnt(0)
	v_add_f32_e32 v25, v25, v28
	v_div_scale_f32 v42, s[24:25], v25, v25, 1.0
	v_rcp_f32_e32 v43, v42
	s_nop 0
	v_fma_f32 v28, -v42, v43, 1.0
	v_fmac_f32_e32 v43, v28, v43
	v_div_scale_f32 v28, vcc, 1.0, v25, 1.0
	v_mul_f32_e32 v194, v28, v43
	v_fma_f32 v195, -v42, v194, v28
	v_fmac_f32_e32 v194, v195, v43
	v_fma_f32 v28, -v42, v194, v28
	s_nop 1
	v_div_fmas_f32 v28, v28, v43, v194
	v_div_fixup_f32 v29, v28, v25, 1.0
	s_movk_i32 s24, 0x7fff
	s_mov_b32 s28, 0x7060302
	v_bfe_u32 v28, v84, 16, 1
	v_add3_u32 v84, v84, v28, s24
	v_bfe_u32 v28, v85, 16, 1
	v_add3_u32 v85, v85, v28, s24
	v_bfe_u32 v28, v86, 16, 1
	v_add3_u32 v86, v86, v28, s24
	v_bfe_u32 v28, v87, 16, 1
	v_add3_u32 v87, v87, v28, s24
	v_bfe_u32 v28, v88, 16, 1
	v_add3_u32 v88, v88, v28, s24
	v_bfe_u32 v28, v89, 16, 1
	v_add3_u32 v89, v89, v28, s24
	v_bfe_u32 v28, v90, 16, 1
	v_add3_u32 v90, v90, v28, s24
	v_bfe_u32 v28, v91, 16, 1
	v_add3_u32 v91, v91, v28, s24
	v_bfe_u32 v28, v44, 16, 1
	v_add3_u32 v44, v44, v28, s24
	v_bfe_u32 v28, v45, 16, 1
	v_add3_u32 v45, v45, v28, s24
	v_bfe_u32 v28, v46, 16, 1
	v_add3_u32 v46, v46, v28, s24
	v_bfe_u32 v28, v47, 16, 1
	v_add3_u32 v47, v47, v28, s24
	v_bfe_u32 v28, v48, 16, 1
	v_add3_u32 v48, v48, v28, s24
	v_bfe_u32 v28, v49, 16, 1
	v_add3_u32 v49, v49, v28, s24
	v_bfe_u32 v28, v50, 16, 1
	v_add3_u32 v50, v50, v28, s24
	v_bfe_u32 v28, v51, 16, 1
	v_add3_u32 v51, v51, v28, s24
	v_bfe_u32 v28, v52, 16, 1
	v_add3_u32 v52, v52, v28, s24
	v_bfe_u32 v28, v53, 16, 1
	v_add3_u32 v53, v53, v28, s24
	v_bfe_u32 v28, v54, 16, 1
	v_add3_u32 v54, v54, v28, s24
	v_bfe_u32 v28, v55, 16, 1
	v_add3_u32 v55, v55, v28, s24
	v_bfe_u32 v28, v56, 16, 1
	v_add3_u32 v56, v56, v28, s24
	v_bfe_u32 v28, v57, 16, 1
	v_add3_u32 v57, v57, v28, s24
	v_bfe_u32 v28, v58, 16, 1
	v_add3_u32 v58, v58, v28, s24
	v_bfe_u32 v28, v59, 16, 1
	v_add3_u32 v59, v59, v28, s24
	v_bfe_u32 v28, v60, 16, 1
	v_add3_u32 v60, v60, v28, s24
	v_bfe_u32 v28, v61, 16, 1
	v_add3_u32 v61, v61, v28, s24
	v_bfe_u32 v28, v62, 16, 1
	v_add3_u32 v62, v62, v28, s24
	v_bfe_u32 v28, v63, 16, 1
	v_add3_u32 v63, v63, v28, s24
	v_bfe_u32 v28, v16, 16, 1
	v_add3_u32 v16, v16, v28, s24
	v_bfe_u32 v28, v17, 16, 1
	v_add3_u32 v17, v17, v28, s24
	v_bfe_u32 v28, v18, 16, 1
	v_add3_u32 v18, v18, v28, s24
	v_bfe_u32 v28, v19, 16, 1
	v_add3_u32 v19, v19, v28, s24
	v_bfe_u32 v28, v20, 16, 1
	v_add3_u32 v20, v20, v28, s24
	v_bfe_u32 v28, v21, 16, 1
	v_add3_u32 v21, v21, v28, s24
	v_bfe_u32 v28, v22, 16, 1
	v_add3_u32 v22, v22, v28, s24
	v_bfe_u32 v28, v23, 16, 1
	v_add3_u32 v23, v23, v28, s24
	v_perm_b32 v87, v87, v86, s28
	v_perm_b32 v86, v85, v84, s28
	v_mov_b32_e32 v84, 0
	v_mov_b32_e32 v85, 0
	v_perm_b32 v88, v89, v88, s28
	v_perm_b32 v89, v91, v90, s28
	v_perm_b32 v90, v45, v44, s28
	v_perm_b32 v91, v47, v46, s28
	v_perm_b32 v48, v49, v48, s28
	v_perm_b32 v49, v51, v50, s28
	v_perm_b32 v50, v53, v52, s28
	v_perm_b32 v51, v55, v54, s28
	v_perm_b32 v56, v57, v56, s28
	v_perm_b32 v57, v59, v58, s28
	v_perm_b32 v58, v61, v60, s28
	v_perm_b32 v59, v63, v62, s28
	v_perm_b32 v16, v17, v16, s28
	v_perm_b32 v17, v19, v18, s28
	v_perm_b32 v18, v21, v20, s28
	v_perm_b32 v19, v23, v22, s28
	s_waitcnt vmcnt(0)
	s_nop 1
	v_mfma_f32_16x16x32_bf16 v[152:155], v[204:207], v[84:87], 0
	v_mfma_f32_16x16x32_bf16 v[156:159], v[224:227], v[84:87], 0
	v_mfma_f32_16x16x32_bf16 v[164:167], v[244:247], v[84:87], 0
	v_mfma_f32_16x16x32_bf16 v[128:131], v[116:119], v[84:87], 0
	v_mfma_f32_16x16x32_bf16 v[152:155], v[208:211], v[88:91], v[152:155]
	v_mfma_f32_16x16x32_bf16 v[156:159], v[228:231], v[88:91], v[156:159]
	v_mfma_f32_16x16x32_bf16 v[164:167], v[248:251], v[88:91], v[164:167]
	v_mfma_f32_16x16x32_bf16 v[128:131], v[120:123], v[88:91], v[128:131]
	v_mfma_f32_16x16x32_bf16 v[152:155], v[212:215], v[48:51], v[152:155]
	v_mfma_f32_16x16x32_bf16 v[156:159], v[232:235], v[48:51], v[156:159]
	v_mfma_f32_16x16x32_bf16 v[164:167], v[104:107], v[48:51], v[164:167]
	v_mfma_f32_16x16x32_bf16 v[128:131], v[124:127], v[48:51], v[128:131]
	v_mfma_f32_16x16x32_bf16 v[152:155], v[216:219], v[56:59], v[152:155]
	v_mfma_f32_16x16x32_bf16 v[156:159], v[236:239], v[56:59], v[156:159]
	v_mfma_f32_16x16x32_bf16 v[164:167], v[108:111], v[56:59], v[164:167]
	v_mfma_f32_16x16x32_bf16 v[128:131], v[76:79], v[56:59], v[128:131]
	v_mfma_f32_16x16x32_bf16 v[152:155], v[220:223], v[16:19], v[152:155]
	v_mfma_f32_16x16x32_bf16 v[156:159], v[240:243], v[16:19], v[156:159]
	v_mfma_f32_16x16x32_bf16 v[164:167], v[112:115], v[16:19], v[164:167]
	v_mfma_f32_16x16x32_bf16 v[128:131], v[80:83], v[16:19], v[128:131]
	s_nop 7
	s_nop 1
	v_mul_f32_e32 v152, v152, v29
	v_mul_f32_e32 v153, v153, v29
	v_mul_f32_e32 v154, v154, v29
	v_mul_f32_e32 v155, v155, v29
	v_bfe_u32 v28, v152, 16, 1
	v_add3_u32 v152, v152, v28, s24
	v_bfe_u32 v28, v153, 16, 1
	v_add3_u32 v153, v153, v28, s24
	v_bfe_u32 v28, v154, 16, 1
	v_add3_u32 v154, v154, v28, s24
	v_bfe_u32 v28, v155, 16, 1
	v_add3_u32 v155, v155, v28, s24
	v_perm_b32 v152, v153, v152, s28
	v_perm_b32 v153, v155, v154, s28
	global_store_dwordx2 v253, v[152:153], s[38:39] offset:0
	v_mul_f32_e32 v156, v156, v29
	v_mul_f32_e32 v157, v157, v29
	v_mul_f32_e32 v158, v158, v29
	v_mul_f32_e32 v159, v159, v29
	v_bfe_u32 v28, v156, 16, 1
	v_add3_u32 v156, v156, v28, s24
	v_bfe_u32 v28, v157, 16, 1
	v_add3_u32 v157, v157, v28, s24
	v_bfe_u32 v28, v158, 16, 1
	v_add3_u32 v158, v158, v28, s24
	v_bfe_u32 v28, v159, 16, 1
	v_add3_u32 v159, v159, v28, s24
	v_perm_b32 v156, v157, v156, s28
	v_perm_b32 v157, v159, v158, s28
	global_store_dwordx2 v253, v[156:157], s[38:39] offset:32
	v_mul_f32_e32 v164, v164, v29
	v_mul_f32_e32 v165, v165, v29
	v_mul_f32_e32 v166, v166, v29
	v_mul_f32_e32 v167, v167, v29
	v_bfe_u32 v28, v164, 16, 1
	v_add3_u32 v164, v164, v28, s24
	v_bfe_u32 v28, v165, 16, 1
	v_add3_u32 v165, v165, v28, s24
	v_bfe_u32 v28, v166, 16, 1
	v_add3_u32 v166, v166, v28, s24
	v_bfe_u32 v28, v167, 16, 1
	v_add3_u32 v167, v167, v28, s24
	v_perm_b32 v164, v165, v164, s28
	v_perm_b32 v165, v167, v166, s28
	global_store_dwordx2 v253, v[164:165], s[38:39] offset:64
	v_mul_f32_e32 v128, v128, v29
	v_mul_f32_e32 v129, v129, v29
	v_mul_f32_e32 v130, v130, v29
	v_mul_f32_e32 v131, v131, v29
	v_bfe_u32 v28, v128, 16, 1
	v_add3_u32 v128, v128, v28, s24
	v_bfe_u32 v28, v129, 16, 1
	v_add3_u32 v129, v129, v28, s24
	v_bfe_u32 v28, v130, 16, 1
	v_add3_u32 v130, v130, v28, s24
	v_bfe_u32 v28, v131, 16, 1
	v_add3_u32 v131, v131, v28, s24
	v_perm_b32 v128, v129, v128, s28
	v_perm_b32 v129, v131, v130, s28
	global_store_dwordx2 v253, v[128:129], s[38:39] offset:96
	v_mov_b32_e32 v65, v24
	v_mov_b32_e32 v68, v25
	v_mov_b32_e32 v38, s27
	s_mul_i32 s24, s29, 0x8080
	v_add_u32_e32 v40, s24, v252
	v_mov_b32_e32 v41, 0
	s_mov_b64 s[64:65], s[6:7]
	s_branch .LBB0_525

; #define MFMA(a, b, c) __builtin_amdgcn_mfma_f32_16x16x32_bf16((a), (b), (c), 0, 0, 0)
; DI u16 f2bf(float x) { unsigned u = __float_as_uint(x); u += 0x7fffu + ((u >> 16) & 1u); return (u16)(u >> 16); }
; DI unsigned pack2(float a, float b) { return (unsigned)f2bf(a) | ((unsigned)f2bf(b) << 16); }
; DI float bflo(unsigned d) { return __uint_as_float(d << 16); }
; DI float bfhi(unsigned d) { return __uint_as_float(d & 0xffff0000u); }
; DI void scan_step(const Params& p, const ScanOps& ops, int n, int b, int h, int s, int j, int lane, f32x4& S0, f32x4& S1,
;                   bf16x8* sSb, u32x2* sUb) {
;   const int r = lane & 15, kg = lane >> 4;
;   bf16x8 sb[4];
; #pragma unroll
;   for (int ks = 0; ks < 4; ++ks) sb[ks] = sSb[ks * 64 + lane];
;   f32x4 u = (f32x4){bflo(ops.u0[0]), bfhi(ops.u0[0]), bflo(ops.u0[1]), bfhi(ops.u0[1])};
; #pragma unroll
;   for (int ks = 0; ks < 4; ++ks) u = MFMA(ops.nW[ks], sb[ks], u);
;   {
;     u32x2 t; t[0] = pack2(u[0], u[1]); t[1] = pack2(u[2], u[3]);
;     sUb[((j >> 1) * 64 + lane) * 2 + (j & 1)] = t;
;   }
;   __syncthreads();
;   bf16x8 ub[2];
; #pragma unroll
;   for (int k2 = 0; k2 < 2; ++k2) ub[k2] = *(const bf16x8*)&sUb[(k2 * 64 + lane) * 2];
;   f32x4 o = (f32x4){0.f, 0.f, 0.f, 0.f};
; #pragma unroll
;   for (int ks = 0; ks < 4; ++ks) o = MFMA(ops.qg[ks], sb[ks], o);
; #pragma unroll
;   for (int k2 = 0; k2 < 2; ++k2) o = MFMA(ops.aq[k2], ub[k2], o);
;   S0 = S0 * ops.dl; S1 = S1 * ops.dl;
; #pragma unroll
;   for (int k2 = 0; k2 < 2; ++k2) { S0 = MFMA(ops.kd[k2], ub[k2], S0); S1 = MFMA(ops.kd[2 + k2], ub[k2], S1); }
;   sSb[j * 64 + lane] = pack8(S0, S1);
; #pragma unroll
;   for (int jj = 0; jj < 4; ++jj) {
;     const size_t token = (size_t)b * SEQ + n * 64 + j * 16 + kg * 4 + jj;
;     G(p.odn)[token * 512 + h * 128 + s * 16 + r] = f2bf(o[jj]);
;   }
;   __syncthreads();
; }
.LBB0_622:
	ds_read_b128 v[206:209], v197
	ds_read_b128 v[210:213], v197 offset:1024
	ds_read_b128 v[128:131], v197 offset:2048
	ds_read_b128 v[124:127], v197 offset:3072
	s_waitcnt vmcnt(16)
	v_lshlrev_b32_e32 v214, 16, v168
	v_and_b32_e32 v215, 0xffff0000, v168
	v_lshlrev_b32_e32 v216, 16, v169
	v_and_b32_e32 v217, 0xffff0000, v169
	v_pk_mul_f32 v[102:103], v[102:103], v[164:165] op_sel_hi:[1,0]
	v_pk_mul_f32 v[100:101], v[100:101], v[164:165] op_sel_hi:[1,0]
	s_waitcnt lgkmcnt(3)
	v_mfma_f32_16x16x32_bf16 v[214:217], v[112:115], v[206:209], v[214:217]
	v_mul_f32_e64 v122, v122, v164
	v_mul_f32_e64 v123, v123, v164
	v_pk_mul_f32 v[120:121], v[120:121], v[164:165] op_sel_hi:[1,0]
	v_or_b32_e32 v112, 0x400, v8
	v_mfma_f32_16x16x32_bf16 v[206:209], v[116:119], v[206:209], 0
	v_mov_b32_e32 v113, v9
	v_or_b32_e32 v114, 0x800, v8
	v_mov_b32_e32 v115, v9
	s_waitcnt lgkmcnt(2)
	v_mfma_f32_16x16x32_bf16 v[214:217], v[104:107], v[210:213], v[214:217]
	v_or_b32_e32 v116, 0xc00, v8
	v_mov_b32_e32 v117, v9
	v_mfma_f32_16x16x32_bf16 v[108:111], v[108:111], v[210:213], v[206:209]
	s_waitcnt lgkmcnt(1)
	v_mfma_f32_16x16x32_bf16 v[96:99], v[96:99], v[128:131], v[214:217]
	s_add_i32 s25, s0, 2
	s_add_i32 s0, s0, 4
	s_min_u32 s0, s0, 0x7f
	v_mfma_f32_16x16x32_bf16 v[84:87], v[84:87], v[128:131], v[108:111]
	s_or_b32 s27, s0, s18
	s_min_u32 s26, s25, 0x7c
	s_mul_i32 s0, s27, 0x12000
	s_waitcnt lgkmcnt(0)
	v_mfma_f32_16x16x32_bf16 v[32:35], v[32:35], v[124:127], v[96:99]
	s_add_i32 s30, s22, s26
	s_add_i32 s26, s18, s26
	s_lshl_b32 s27, s27, 2
	v_mfma_f32_16x16x32_bf16 v[84:87], v[88:91], v[124:127], v[84:87]
	s_lshl_b32 s31, s26, 2
	s_nop 2
	v_bfe_u32 v88, v32, 16, 1
	v_bfe_u32 v90, v34, 16, 1
	v_bfe_u32 v89, v33, 16, 1
	v_bfe_u32 v91, v35, 16, 1
	v_add3_u32 v32, v32, v88, s24
	v_add3_u32 v34, v34, v90, s24
	v_add3_u32 v33, v33, v89, s24
	v_add3_u32 v35, v35, v91, s24
	v_lshrrev_b32_e32 v32, 16, v32
	v_lshrrev_b32_e32 v34, 16, v34
	v_and_or_b32 v32, v33, s23, v32
	v_and_or_b32 v33, v35, s23, v34
	ds_write_b64 v147, v[32:33] offset:4096
	s_waitcnt lgkmcnt(0)
	s_barrier
	ds_read_b128 v[32:35], v197 offset:4096
	ds_read_b128 v[88:91], v197 offset:5120
	s_waitcnt lgkmcnt(1)
	v_mfma_f32_16x16x32_bf16 v[16:19], v[16:19], v[32:35], v[100:103]
	v_or_b32_e32 v218, 0x400, v152
	v_mov_b32_e32 v219, v153
	v_or_b32_e32 v194, 0x800, v152
	v_mfma_f32_16x16x32_bf16 v[20:23], v[20:23], v[32:35], v[120:123]
	v_mov_b32_e32 v195, v153
	v_or_b32_e32 v128, 0xc00, v152
	v_mov_b32_e32 v129, v153
	v_mfma_f32_16x16x32_bf16 v[40:43], v[40:43], v[32:35], v[84:87]
	ds_read_b64 v[32:33], v149
	s_cmpk_lt_u32 s25, 0x7e
	s_waitcnt lgkmcnt(0)
	v_lshl_add_u64 v[34:35], v[32:33], 0, s[12:13]
	v_mfma_f32_16x16x32_bf16 v[100:103], v[4:7], v[88:91], v[16:19]
	v_lshl_add_u64 v[34:35], v[34:35], 0, s[14:15]
	v_lshl_add_u64 v[34:35], v[34:35], 0, v[156:157]
	v_lshl_add_u64 v[4:5], v[34:35], 0, v[112:113]
	v_mfma_f32_16x16x32_bf16 v[120:123], v[12:15], v[88:91], v[20:23]
	v_lshl_add_u64 v[6:7], v[34:35], 0, v[114:115]
	s_nop 2
	v_bfe_u32 v12, v100, 16, 1
	v_bfe_u32 v14, v102, 16, 1
	v_mfma_f32_16x16x32_bf16 v[0:3], v[0:3], v[88:91], v[40:43]
	v_lshl_add_u64 v[16:17], v[34:35], 0, v[116:117]
	v_bfe_u32 v18, v120, 16, 1
	v_bfe_u32 v20, v122, 16, 1
	v_bfe_u32 v13, v101, 16, 1
	v_bfe_u32 v15, v103, 16, 1
	v_bfe_u32 v19, v121, 16, 1
	v_bfe_u32 v21, v123, 16, 1
	s_nop 0
	v_bfe_u32 v22, v0, 16, 1
	v_bfe_u32 v23, v1, 16, 1
	v_bfe_u32 v34, v2, 16, 1
	v_bfe_u32 v35, v3, 16, 1
	v_add3_u32 v12, v100, v12, s24
	v_add3_u32 v14, v102, v14, s24
	v_add3_u32 v18, v120, v18, s24
	v_add3_u32 v20, v122, v20, s24
	v_lshl_add_u64 v[32:33], v[32:33], 0, v[154:155]
	v_add3_u32 v13, v101, v13, s24
	v_add3_u32 v15, v103, v15, s24
	v_add3_u32 v19, v121, v19, s24
	v_add3_u32 v21, v123, v21, s24
	v_add3_u32 v22, v0, v22, s24
	v_add3_u32 v23, v1, v23, s24
	v_add3_u32 v34, v2, v34, s24
	v_add3_u32 v35, v3, v35, s24
	v_lshrrev_b32_e32 v0, 16, v12
	v_lshrrev_b32_e32 v1, 16, v14
	v_lshrrev_b32_e32 v2, 16, v18
	v_lshrrev_b32_e32 v3, 16, v20
	v_lshl_add_u64 v[32:33], v[32:33], 0, v[8:9]
	v_and_or_b32 v0, v13, s23, v0
	v_and_or_b32 v1, v15, s23, v1
	v_and_or_b32 v2, v19, s23, v2
	v_and_or_b32 v3, v21, s23, v3
	ds_write_b128 v151, v[0:3]
	flat_store_short_d16_hi v[32:33], v22
	flat_store_short_d16_hi v[4:5], v23
	flat_store_short_d16_hi v[6:7], v34
	flat_store_short_d16_hi v[16:17], v35
	s_waitcnt lgkmcnt(0)
	s_barrier
; #define MFMA(a, b, c) __builtin_amdgcn_mfma_f32_16x16x32_bf16((a), (b), (c), 0, 0, 0)
; #define AS1 __attribute__((address_space(1)))
; DI float bflo(unsigned d) { return __uint_as_float(d << 16); }
; DI float bfhi(unsigned d) { return __uint_as_float(d & 0xffff0000u); }
; DI void scan_load(const Params& p, int bh, int s, int n, int j, int lane, ScanOps& o) {
;   n = n > 127 ? 127 : n;
;   const char AS1* base = (const char AS1*)p.dnops + (size_t)(bh * 128 + n) * DN_ITEM;
;   gb8p negW = (gb8p)base;
;   gb8p qg = (gb8p)(base + 16384);
;   gb8p kdT = (gb8p)(base + 32768);
;   gb8p aqk = (gb8p)(base + 49152);
;   const u32x2 AS1* u0 = (const u32x2 AS1*)(base + 57344);
; #pragma unroll
;   for (int ks = 0; ks < 4; ++ks) o.nW[ks] = negW[(j * 4 + ks) * 64 + lane];
; #pragma unroll
;   for (int ks = 0; ks < 4; ++ks) o.qg[ks] = qg[(j * 4 + ks) * 64 + lane];
; #pragma unroll
;   for (int k2 = 0; k2 < 2; ++k2) o.aq[k2] = aqk[(j * 2 + k2) * 64 + lane];
; #pragma unroll
;   for (int mm = 0; mm < 2; ++mm)
; #pragma unroll
;     for (int k2 = 0; k2 < 2; ++k2) o.kd[mm * 2 + k2] = kdT[((2 * j + mm) * 2 + k2) * 64 + lane];
;   o.u0 = u0[(s * 4 + j) * 64 + lane];
;   o.dl = ((const float AS1*)p.dl)[bh * 128 + n];
; }
; DI void scan_step(const Params& p, const ScanOps& ops, int n, int b, int h, int s, int j, int lane, f32x4& S0, f32x4& S1,
;                   bf16x8* sSb, u32x2* sUb) {
;   const int r = lane & 15, kg = lane >> 4;
;   bf16x8 sb[4];
; #pragma unroll
;   for (int ks = 0; ks < 4; ++ks) sb[ks] = sSb[ks * 64 + lane];
;   f32x4 u = (f32x4){bflo(ops.u0[0]), bfhi(ops.u0[0]), bflo(ops.u0[1]), bfhi(ops.u0[1])};
; #pragma unroll
;   for (int ks = 0; ks < 4; ++ks) u = MFMA(ops.nW[ks], sb[ks], u);
	ds_read_b128 v[0:3], v197
	ds_read_b64 v[20:21], v141
	ds_read_b64 v[22:23], v145
	ds_read_b128 v[4:7], v197 offset:1024
	ds_read_b128 v[12:15], v197 offset:2048
	ds_read_b128 v[124:127], v197 offset:3072
	s_waitcnt vmcnt(4)
	v_lshlrev_b32_e32 v104, 16, v166
	v_and_b32_e32 v105, 0xffff0000, v166
	v_lshlrev_b32_e32 v106, 16, v167
	v_and_b32_e32 v107, 0xffff0000, v167
	s_waitcnt lgkmcnt(0)
	s_nop 0
	v_mfma_f32_16x16x32_bf16 v[16:19], v[72:75], v[0:3], v[104:107]
	v_lshl_add_u64 v[20:21], v[20:21], 0, s[0:1]
	v_mov_b32_e32 v84, s27
	v_readfirstlane_b32 s26, v22
	v_mfma_f32_16x16x32_bf16 v[0:3], v[92:95], v[0:3], 0
	v_readfirstlane_b32 s27, v23
	v_lshl_add_u64 v[40:41], v[20:21], 0, s[8:9]
	v_lshl_add_u64 v[42:43], v[20:21], 0, v[158:159]
	v_mfma_f32_16x16x32_bf16 v[16:19], v[56:59], v[4:7], v[16:19]
	v_readfirstlane_b32 s28, v20
	v_readfirstlane_b32 s29, v21
	global_load_dword v164, v84, s[26:27]
	s_nop 3
	global_load_dwordx4 v[112:115], v198, s[28:29]
	global_load_dwordx4 v[104:107], v198, s[28:29] offset:1024
	global_load_dwordx4 v[96:99], v198, s[28:29] offset:2048
	global_load_dwordx4 v[32:35], v198, s[28:29] offset:3072
	v_mfma_f32_16x16x32_bf16 v[4:7], v[76:79], v[4:7], v[0:3]
	v_readfirstlane_b32 s26, v40
	v_add_co_u32_e32 v40, vcc, s19, v42
	v_mfma_f32_16x16x32_bf16 v[48:51], v[48:51], v[12:15], v[16:19]
	v_lshl_add_u64 v[22:23], v[20:21], 0, s[2:3]
	v_lshl_add_u64 v[20:21], v[20:21], 0, v[160:161]
	v_readfirstlane_b32 s27, v41
	v_mfma_f32_16x16x32_bf16 v[56:59], v[80:83], v[12:15], v[4:7]
	v_addc_co_u32_e32 v41, vcc, 0, v43, vcc
	v_readfirstlane_b32 s28, v22
	v_mfma_f32_16x16x32_bf16 v[28:31], v[28:31], v[124:127], v[48:51]
	v_readfirstlane_b32 s29, v23
	v_add_co_u32_e32 v74, vcc, s20, v20
	v_mfma_f32_16x16x32_bf16 v[48:51], v[68:71], v[124:127], v[56:59]
	v_lshl_add_u64 v[72:73], v[42:43], 0, s[10:11]
	v_addc_co_u32_e32 v75, vcc, 0, v21, vcc
	s_nop 2
	v_bfe_u32 v56, v28, 16, 1
	v_bfe_u32 v58, v30, 16, 1
	v_bfe_u32 v57, v29, 16, 1
	v_bfe_u32 v59, v31, 16, 1
	v_add3_u32 v28, v28, v56, s24
	v_add3_u32 v30, v30, v58, s24
	v_add3_u32 v29, v29, v57, s24
	v_add3_u32 v31, v31, v59, s24
	v_lshrrev_b32_e32 v28, 16, v28
	v_lshrrev_b32_e32 v30, 16, v30
	v_and_or_b32 v28, v29, s23, v28
	v_and_or_b32 v29, v31, s23, v30
	global_load_dwordx4 v[84:87], v202, s[26:27]
	global_load_dwordx4 v[88:91], v204, s[26:27]
	s_nop 0
	global_load_dwordx4 v[40:43], v[40:41], off
	s_nop 0
	global_load_dwordx4 v[0:3], v[72:73], off offset:1024
	global_load_dwordx4 v[16:19], v198, s[28:29]
	global_load_dwordx4 v[4:7], v198, s[28:29] offset:1024
	global_load_dwordx4 v[108:111], v201, s[26:27]
	global_load_dwordx4 v[20:23], v202, s[28:29]
	global_load_dwordx4 v[116:119], v198, s[26:27]
	global_load_dwordx4 v[12:15], v198, s[28:29] offset:3072
	global_load_dwordx2 v[168:169], v[74:75], off
	ds_write_b64 v147, v[28:29] offset:4096
	s_waitcnt lgkmcnt(0)
	s_barrier
; #define MFMA(a, b, c) __builtin_amdgcn_mfma_f32_16x16x32_bf16((a), (b), (c), 0, 0, 0)
; DI u16 f2bf(float x) { unsigned u = __float_as_uint(x); u += 0x7fffu + ((u >> 16) & 1u); return (u16)(u >> 16); }
; DI void scan_step(const Params& p, const ScanOps& ops, int n, int b, int h, int s, int j, int lane, f32x4& S0, f32x4& S1,
;                   bf16x8* sSb, u32x2* sUb) {
;     ...
;   __syncthreads();
;   bf16x8 ub[2];
; #pragma unroll
;   for (int k2 = 0; k2 < 2; ++k2) ub[k2] = *(const bf16x8*)&sUb[(k2 * 64 + lane) * 2];
;   f32x4 o = (f32x4){0.f, 0.f, 0.f, 0.f};
; #pragma unroll
;   for (int ks = 0; ks < 4; ++ks) o = MFMA(ops.qg[ks], sb[ks], o);
; #pragma unroll
;   for (int k2 = 0; k2 < 2; ++k2) o = MFMA(ops.aq[k2], ub[k2], o);
;   S0 = S0 * ops.dl; S1 = S1 * ops.dl;
; #pragma unroll
;   for (int k2 = 0; k2 < 2; ++k2) { S0 = MFMA(ops.kd[k2], ub[k2], S0); S1 = MFMA(ops.kd[2 + k2], ub[k2], S1); }
;   sSb[j * 64 + lane] = pack8(S0, S1);
; #pragma unroll
;   for (int jj = 0; jj < 4; ++jj) {
;     const size_t token = (size_t)b * SEQ + n * 64 + j * 16 + kg * 4 + jj;
;     G(p.odn)[token * 512 + h * 128 + s * 16 + r] = f2bf(o[jj]);
;   }
;   __syncthreads();
; }
; DI void dn_scan_block(const Params& p, int item, char* smem) {
;     ...
;   for (int n0 = 0; n0 < 128; n0 += 2) {
;     scan_step(p, A, n0, b, h, s, j, lane, S0, S1, sSb, sUb);
;     scan_load(p, bh, s, n0 + 2, j, lane, A);
;     scan_step(p, B, n0 + 1, b, h, s, j, lane, S0, S1, sSb, sUb);
;     scan_load(p, bh, s, n0 + 3, j, lane, B);
;   }
; #pragma unroll
;   for (int jj = 0; jj < 4; ++jj) {
;     p.out[O_PDELTA + ((size_t)bh * 128 + 32 * j + kg * 4 + jj) * 128 + s * 16 + r] = S0[jj];
;     p.out[O_PDELTA + ((size_t)bh * 128 + 32 * j + 16 + kg * 4 + jj) * 128 + s * 16 + r] = S1[jj];
;   }
	ds_read_b128 v[28:31], v197 offset:4096
	ds_read_b128 v[56:59], v197 offset:5120
	s_waitcnt lgkmcnt(0)
	v_mfma_f32_16x16x32_bf16 v[48:51], v[52:55], v[28:31], v[48:51]
	v_mul_f32_e64 v54, v162, v102
	v_mul_f32_e64 v55, v162, v103
	v_pk_mul_f32 v[52:53], v[162:163], v[100:101] op_sel_hi:[0,1]
	s_mul_i32 s0, s30, 0x12000
	v_mfma_f32_16x16x32_bf16 v[24:27], v[24:27], v[56:59], v[48:51]
	v_mov_b32_e32 v68, s31
	v_lshl_add_u64 v[8:9], v[8:9], 0, s[16:17]
	v_mfma_f32_16x16x32_bf16 v[52:55], v[60:63], v[28:31], v[52:55]
	v_mul_f32_e64 v62, v162, v122
	v_mul_f32_e64 v63, v162, v123
	v_pk_mul_f32 v[60:61], v[162:163], v[120:121] op_sel_hi:[0,1]
	v_mfma_f32_16x16x32_bf16 v[100:103], v[36:39], v[56:59], v[52:55]
	s_nop 0
	v_mfma_f32_16x16x32_bf16 v[28:31], v[64:67], v[28:31], v[60:63]
	s_nop 1
	v_bfe_u32 v52, v24, 16, 1
	v_bfe_u32 v53, v25, 16, 1
	v_bfe_u32 v54, v26, 16, 1
	ds_read_b64 v[60:61], v149
	v_mfma_f32_16x16x32_bf16 v[120:123], v[44:47], v[56:59], v[28:31]
	v_bfe_u32 v55, v27, 16, 1
	v_add3_u32 v52, v24, v52, s24
	v_add3_u32 v53, v25, v53, s24
	v_bfe_u32 v28, v100, 16, 1
	v_bfe_u32 v30, v102, 16, 1
	s_nop 2
	v_bfe_u32 v44, v120, 16, 1
	v_bfe_u32 v46, v122, 16, 1
	s_waitcnt lgkmcnt(0)
	v_lshl_add_u64 v[62:63], v[60:61], 0, s[12:13]
	v_bfe_u32 v29, v101, 16, 1
	v_bfe_u32 v31, v103, 16, 1
	v_bfe_u32 v45, v121, 16, 1
	v_bfe_u32 v47, v123, 16, 1
	v_add3_u32 v28, v100, v28, s24
	v_add3_u32 v30, v102, v30, s24
	v_add3_u32 v44, v120, v44, s24
	v_add3_u32 v46, v122, v46, s24
	v_lshl_add_u64 v[60:61], v[60:61], 0, v[154:155]
	v_lshl_add_u64 v[48:49], v[62:63], 0, s[14:15]
	v_add3_u32 v29, v101, v29, s24
	v_add3_u32 v31, v103, v31, s24
	v_add3_u32 v45, v121, v45, s24
	v_add3_u32 v47, v123, v47, s24
	v_add3_u32 v54, v26, v54, s24
	v_add3_u32 v55, v27, v55, s24
	v_lshrrev_b32_e32 v24, 16, v28
	v_lshrrev_b32_e32 v25, 16, v30
	v_lshrrev_b32_e32 v26, 16, v44
	v_lshrrev_b32_e32 v27, 16, v46
	v_lshl_add_u64 v[50:51], v[60:61], 0, v[152:153]
	v_lshl_add_u64 v[48:49], v[48:49], 0, v[156:157]
	v_and_or_b32 v24, v29, s23, v24
	v_and_or_b32 v25, v31, s23, v25
	v_and_or_b32 v26, v45, s23, v26
	v_and_or_b32 v27, v47, s23, v27
	v_lshl_add_u64 v[36:37], v[48:49], 0, v[218:219]
	v_lshl_add_u64 v[38:39], v[48:49], 0, v[194:195]
	v_lshl_add_u64 v[48:49], v[48:49], 0, v[128:129]
	ds_write_b128 v151, v[24:27]
	flat_store_short_d16_hi v[50:51], v52
	flat_store_short_d16_hi v[36:37], v53
	flat_store_short_d16_hi v[38:39], v54
	flat_store_short_d16_hi v[48:49], v55
	s_waitcnt lgkmcnt(0)
	s_barrier
	ds_read_b64 v[24:25], v141
	ds_read_b64 v[26:27], v145
	v_lshl_add_u64 v[152:153], v[152:153], 0, s[16:17]
	s_waitcnt lgkmcnt(0)
	v_lshl_add_u64 v[24:25], v[24:25], 0, s[0:1]
	v_readfirstlane_b32 s26, v26
	v_readfirstlane_b32 s27, v27
	v_lshl_add_u64 v[36:37], v[24:25], 0, s[8:9]
	v_lshl_add_u64 v[38:39], v[24:25], 0, v[158:159]
	v_readfirstlane_b32 s28, v24
	v_readfirstlane_b32 s29, v25
	s_nop 0
	global_load_dword v162, v68, s[26:27] offset:12
	s_nop 2
	global_load_dwordx4 v[72:75], v198, s[28:29]
	global_load_dwordx4 v[56:59], v198, s[28:29] offset:1024
	global_load_dwordx4 v[48:51], v198, s[28:29] offset:2048
	global_load_dwordx4 v[28:31], v198, s[28:29] offset:3072
	v_readfirstlane_b32 s26, v36
	v_readfirstlane_b32 s27, v37
	v_lshl_add_u64 v[36:37], v[38:39], 0, s[10:11]
	v_add_co_u32_e32 v38, vcc, s19, v38
	v_lshl_add_u64 v[26:27], v[24:25], 0, s[2:3]
	v_lshl_add_u64 v[24:25], v[24:25], 0, v[160:161]
	v_addc_co_u32_e32 v39, vcc, 0, v39, vcc
	v_add_co_u32_e32 v124, vcc, s20, v24
	v_readfirstlane_b32 s28, v26
	v_readfirstlane_b32 s29, v27
	v_addc_co_u32_e32 v125, vcc, 0, v25, vcc
	global_load_dwordx4 v[80:83], v202, s[26:27]
	global_load_dwordx4 v[68:71], v204, s[26:27]
	global_load_dwordx4 v[52:55], v[38:39], off
	global_load_dwordx4 v[24:27], v[36:37], off offset:1024
	global_load_dwordx4 v[60:63], v198, s[28:29]
	s_nop 0
	global_load_dwordx4 v[36:39], v198, s[28:29] offset:1024
	global_load_dwordx4 v[76:79], v201, s[26:27]
	global_load_dwordx4 v[64:67], v202, s[28:29]
	global_load_dwordx4 v[92:95], v198, s[26:27]
	global_load_dwordx4 v[44:47], v198, s[28:29] offset:3072
	global_load_dwordx2 v[166:167], v[124:125], off
	s_mov_b32 s0, s25
	s_cbranch_scc1 .LBB0_622
	s_waitcnt vmcnt(0)
	v_mov_b32_e32 v0, 0x100d8
	ds_read_b64 v[0:1], v0
	v_add_u32_e32 v2, s18, v178
	v_or_b32_e32 v2, v2, v200
	v_lshlrev_b32_e32 v2, 9, v2
	v_mov_b32_e32 v3, 0
	s_mov_b32 s1, 0
	s_waitcnt lgkmcnt(0)
	v_lshl_add_u64 v[0:1], v[0:1], 0, v[2:3]
	s_lshl_b32 s0, s21, 2
	v_mov_b32_e32 v151, v3
	v_lshl_add_u64 v[0:1], v[0:1], 0, s[0:1]
	v_lshl_add_u64 v[0:1], v[0:1], 0, v[150:151]
	v_add_co_u32_e32 v2, vcc, 0x8080000, v0
	s_nop 1
	v_addc_co_u32_e32 v3, vcc, 0, v1, vcc
	v_add_co_u32_e32 v0, vcc, 0x8082000, v0
	flat_store_dword v[2:3], v100
	s_nop 0
	v_addc_co_u32_e32 v1, vcc, 0, v1, vcc
	flat_store_dword v[0:1], v120
	flat_store_dword v[2:3], v101 offset:512
	flat_store_dword v[0:1], v121 offset:512
	flat_store_dword v[2:3], v102 offset:1024
	flat_store_dword v[0:1], v122 offset:1024
	flat_store_dword v[2:3], v103 offset:1536
	flat_store_dword v[0:1], v123 offset:1536
